# v28 + window interior tile: kb=1 K fragments requested up front, QK chains back to back
# speedup vs baseline: 1.0032x; 1.0006x over previous
.LBB0_868:
	s_and_b64 vcc, exec, s[18:19]
	s_cbranch_vccz .LBB0_872
	ds_read_b128 v[238:241], v126 offset:4608
	ds_read_b128 v[242:245], v126 offset:4640
	ds_read_b128 v[246:249], v126 offset:4672
	ds_read_b128 v[250:253], v126 offset:4704
	v_mov_b32_e32 v0, v123
	s_waitcnt lgkmcnt(7)
	v_mfma_f32_32x32x16_bf16 v[50:65], v[110:113], v[66:69], 0
	v_cvt_f32_i32_e32 v110, v0
	s_waitcnt lgkmcnt(6)
	v_mfma_f32_32x32x16_bf16 v[50:65], v[106:109], v[70:73], v[50:65]
	s_waitcnt lgkmcnt(5)
	v_mfma_f32_32x32x16_bf16 v[50:65], v[98:101], v[74:77], v[50:65]
	s_waitcnt lgkmcnt(4)
	v_mfma_f32_32x32x16_bf16 v[50:65], v[102:105], v[78:81], v[50:65]
	s_waitcnt lgkmcnt(3)
	v_mfma_f32_32x32x16_bf16 v[34:49], v[238:241], v[66:69], 0
	s_waitcnt lgkmcnt(2)
	v_mfma_f32_32x32x16_bf16 v[34:49], v[242:245], v[70:73], v[34:49]
	s_waitcnt lgkmcnt(1)
	v_mfma_f32_32x32x16_bf16 v[34:49], v[246:249], v[74:77], v[34:49]
	s_waitcnt lgkmcnt(0)
	v_mfma_f32_32x32x16_bf16 v[34:49], v[250:253], v[78:81], v[34:49]
	s_nop 3
	v_add_f32_e32 v109, v148, v50
	v_add_f32_e32 v108, v118, v51
	v_max3_f32 v0, v109, s28, v108
	v_add_f32_e32 v107, v149, v52
	v_add_f32_e32 v106, v150, v53
	v_max3_f32 v0, v0, v107, v106
	v_add_f32_e32 v105, v151, v54
	v_add_f32_e32 v104, v152, v55
	v_max3_f32 v0, v0, v105, v104
	v_add_f32_e32 v103, v153, v56
	v_add_f32_e32 v102, v154, v57
	v_max3_f32 v0, v0, v103, v102
	v_add_f32_e32 v101, v155, v58
	v_add_f32_e32 v100, v156, v59
	v_max3_f32 v0, v0, v101, v100
	v_add_f32_e32 v99, v157, v60
	v_add_f32_e32 v98, v158, v61
	v_max3_f32 v0, v0, v99, v98
	v_add_f32_e32 v61, v159, v62
	v_add_f32_e32 v60, v160, v63
	v_max3_f32 v0, v0, v61, v60
	v_add_f32_e32 v59, v161, v64
	v_add_f32_e32 v58, v162, v65
	v_max3_f32 v0, v0, v59, v58
	v_add_f32_e32 v57, v163, v34
	v_add_f32_e32 v56, v166, v35
	v_max3_f32 v0, v0, v57, v56
	v_add_f32_e32 v55, v167, v36
	v_add_f32_e32 v54, v168, v37
	v_max3_f32 v0, v0, v55, v54
	v_add_f32_e32 v53, v169, v38
	v_add_f32_e32 v52, v170, v39
	v_max3_f32 v0, v0, v53, v52
	v_add_f32_e32 v51, v171, v40
	v_add_f32_e32 v50, v172, v41
	v_max3_f32 v0, v0, v51, v50
	v_add_f32_e32 v41, v173, v42
	v_add_f32_e32 v40, v174, v43
	v_max3_f32 v0, v0, v41, v40
	v_add_f32_e32 v39, v175, v44
	v_add_f32_e32 v38, v176, v45
	v_and_b32_e32 v43, 64, v228
	v_max3_f32 v0, v0, v39, v38
	v_add_f32_e32 v37, v177, v46
	v_add_f32_e32 v36, v178, v47
	v_xor_b32_e32 v42, 32, v228
	v_add_u32_e32 v43, 64, v43
	v_max3_f32 v0, v0, v37, v36
	v_add_f32_e32 v35, v179, v48
	v_add_f32_e32 v34, v180, v49
	v_cmp_lt_i32_e32 vcc, v42, v43
	v_max3_f32 v0, v0, v35, v34
	v_fma_f32 v0, -v118, v110, v0
	v_cndmask_b32_e32 v42, v228, v42, vcc
	v_lshlrev_b32_e32 v42, 2, v42
	ds_bpermute_b32 v42, v42, v0
	s_waitcnt lgkmcnt(0)
	v_max3_f32 v0, v125, v0, v42
	v_cmp_gt_f32_e32 vcc, v0, v125
	s_cbranch_vccz .LBB0_871
	v_sub_f32_e32 v42, v125, v0
	v_exp_f32_e32 v42, v42
	s_nop 0
	v_mul_f32_e32 v124, v124, v42
	v_pk_mul_f32 v[32:33], v[32:33], v[42:43] op_sel_hi:[1,0]
	v_pk_mul_f32 v[30:31], v[30:31], v[42:43] op_sel_hi:[1,0]
	v_pk_mul_f32 v[28:29], v[28:29], v[42:43] op_sel_hi:[1,0]
	v_pk_mul_f32 v[26:27], v[26:27], v[42:43] op_sel_hi:[1,0]
	v_pk_mul_f32 v[24:25], v[24:25], v[42:43] op_sel_hi:[1,0]
	v_pk_mul_f32 v[22:23], v[22:23], v[42:43] op_sel_hi:[1,0]
	v_pk_mul_f32 v[20:21], v[20:21], v[42:43] op_sel_hi:[1,0]
	v_pk_mul_f32 v[18:19], v[18:19], v[42:43] op_sel_hi:[1,0]
	v_pk_mul_f32 v[16:17], v[16:17], v[42:43] op_sel_hi:[1,0]
	v_pk_mul_f32 v[14:15], v[14:15], v[42:43] op_sel_hi:[1,0]
	v_pk_mul_f32 v[12:13], v[12:13], v[42:43] op_sel_hi:[1,0]
	v_pk_mul_f32 v[10:11], v[10:11], v[42:43] op_sel_hi:[1,0]
	v_pk_mul_f32 v[8:9], v[8:9], v[42:43] op_sel_hi:[1,0]
	v_pk_mul_f32 v[6:7], v[6:7], v[42:43] op_sel_hi:[1,0]
	v_pk_mul_f32 v[4:5], v[4:5], v[42:43] op_sel_hi:[1,0]
	v_pk_mul_f32 v[2:3], v[2:3], v[42:43] op_sel_hi:[1,0]
